# prep tail loops de-serialised (x copy 16 loads in flight, state shifts dwordx4 all in flight); LN loop-top vmcnt(0) moved to preheader; sample_item state-row loads all issued up front
# speedup vs baseline: 1.0314x; 1.0161x over previous
; #define LAS __attribute__((address_space(3)))
; DI const float* INP(const Args& a, int i) { asm volatile("" : "+s"(i)); return a.in[i]; }
; DI void sample_item(LAS unsigned char* lds, const Args& a, int l, int item) {
;     ...
;     const float qsc = rsqrtf(red3[0] + 1e-6f) * 0.08838834764831845f, ksc = rsqrtf(red3[1] + 1e-6f), qkdot = red3[2] * qsc * ksc;
;     const float beta = ((const float*)(a.ws + WS_BETA))[(size_t)row * 4 + h], ga = expf(((const float*)(a.ws + WS_G))[(size_t)row * 4 + h]);
;     const int dv4 = tid & 31, dkg = tid >> 5;
;     const float* S0 = INP(a, 2) + (size_t)((l * 128 + b) * 4 + h) * 16384;
;     f32x4 S[8]; f32x4 ks4 = {0.f, 0.f, 0.f, 0.f}, qs4 = {0.f, 0.f, 0.f, 0.f};
; #pragma unroll
;     for (int j = 0; j < 8; ++j) { const int dk = dkg * 8 + j; S[j] = __builtin_nontemporal_load((const f32x4*)(S0 + dk * 128 + dv4 * 4)); const float kk = vals[128 + dk] * ksc, qq = vals[dk] * qsc; ks4 += S[j] * kk; qs4 += S[j] * qq; }
;     *(LAS f32x4*)(red + (dkg * 128 + dv4 * 4) * 2) = ks4; *(LAS f32x4*)(red + (dkg * 128 + dv4 * 4) * 2 + 4) = qs4;
.LBB0_216:
	s_or_b64 exec, exec, s[12:13]
	s_ashr_i32 s9, s8, 31
	s_lshl_b32 s14, s36, 2
	s_lshl_b64 s[12:13], s[8:9], 4
	s_or_b32 s12, s12, s14
	v_readlane_b32 s14, v254, 12
	s_waitcnt lgkmcnt(0)
	s_barrier
	ds_read_b96 v[38:40], v129 offset:1536
	v_readlane_b32 s15, v254, 13
	s_add_u32 s14, s14, s12
	s_addc_u32 s15, s15, s13
	v_ashrrev_i32_e32 v45, 5, v41
	v_and_b32_e32 v66, 31, v41
	s_waitcnt vmcnt(0)
	v_lshlrev_b32_e32 v18, 10, v45
	global_load_dword v44, v129, s[14:15]
	v_readlane_b32 s14, v254, 14
	v_readlane_b32 s15, v254, 15
	s_add_u32 s12, s14, s12
	s_addc_u32 s13, s15, s13
	global_load_dword v68, v129, s[12:13]
	s_waitcnt lgkmcnt(0)
	v_add_f32_e32 v0, 0x358637bd, v38
	v_cmp_gt_f32_e32 vcc, s46, v0
	v_mul_f32_e32 v1, 0x4b800000, v0
	s_mov_b32 s12, 2
	v_cndmask_b32_e32 v0, v0, v1, vcc
	v_rsq_f32_e32 v0, v0
	s_ashr_i32 s13, s12, 31
	s_lshl_b64 s[12:13], s[12:13], 3
	v_mul_f32_e32 v1, 0x45800000, v0
	s_add_u32 s12, s0, s12
	v_cndmask_b32_e32 v0, v0, v1, vcc
	s_addc_u32 s13, s1, s13
	v_mul_f32_e32 v64, 0x3db504f3, v0
	v_add_f32_e32 v0, 0x358637bd, v39
	s_load_dwordx2 s[14:15], s[12:13], 0x0
	s_and_b32 s12, s35, -4
	v_cmp_gt_f32_e32 vcc, s46, v0
	v_mul_f32_e32 v1, 0x4b800000, v0
	s_add_i32 s12, s12, s10
	v_cndmask_b32_e32 v0, v0, v1, vcc
	s_or_b32 s12, s12, s36
	v_rsq_f32_e32 v0, v0
	s_ashr_i32 s13, s12, 31
	s_lshl_b64 s[12:13], s[12:13], 16
	s_waitcnt lgkmcnt(0)
	s_add_u32 s14, s14, s12
	s_addc_u32 s15, s15, s13
	v_lshlrev_b32_e32 v128, 4, v66
	v_ashrrev_i32_e32 v19, 31, v18
	v_mul_f32_e32 v1, 0x45800000, v0
	v_lshl_add_u64 v[16:17], s[14:15], 0, v[128:129]
	v_lshlrev_b64 v[48:49], 2, v[18:19]
	v_or_b32_e32 v20, 0x80, v18
	v_cndmask_b32_e32 v65, v0, v1, vcc
	v_lshl_add_u64 v[0:1], v[16:17], 0, v[48:49]
	v_ashrrev_i32_e32 v21, 31, v20
	global_load_dwordx4 v[8:11], v[0:1], off nt
	v_mov_b64_e32 v[112:113], v[0:1]
	v_and_b32_e32 v0, 0xffffffe0, v41
	v_lshlrev_b64 v[50:51], 2, v[20:21]
	v_add_u32_e32 v67, 0, v0
	v_lshl_add_u64 v[20:21], v[16:17], 0, v[50:51]
	ds_read_b128 v[0:3], v67 offset:512
	ds_read_b128 v[4:7], v67
	ds_read_b128 v[32:35], v67 offset:16
	global_load_dwordx4 v[20:23], v[20:21], off nt
	v_or_b32_e32 v28, 0x180, v18
	v_ashrrev_i32_e32 v29, 31, v28
	s_waitcnt lgkmcnt(2)
	v_mul_f32_e32 v0, v65, v0
	s_waitcnt lgkmcnt(1)
	v_mul_f32_e32 v4, v64, v4
	v_lshlrev_b64 v[54:55], 2, v[28:29]
	v_lshl_add_u64 v[28:29], v[16:17], 0, v[54:55]
	global_load_dwordx4 v[28:31], v[28:29], off nt
	global_load_dwordx4 v[92:95], v[112:113], off offset:1024 nt
	global_load_dwordx4 v[96:99], v[112:113], off offset:2048 nt
	global_load_dwordx4 v[100:103], v[112:113], off offset:2560 nt
	global_load_dwordx4 v[104:107], v[112:113], off offset:3072 nt
	global_load_dwordx4 v[108:111], v[112:113], off offset:3584 nt
	v_mul_f32_e32 v2, v65, v2
	ds_read_b128 v[36:39], v67 offset:528
	v_mul_f32_e32 v6, v64, v6
	s_waitcnt lgkmcnt(1)
	v_mul_f32_e32 v32, v64, v32
	v_mul_f32_e32 v34, v64, v34
	s_mov_b32 s14, 0x3fb8aa3b
	s_waitcnt lgkmcnt(0)
	v_mul_f32_e32 v38, v65, v38
	s_waitcnt vmcnt(7)
	v_pk_fma_f32 v[12:13], v[10:11], v[0:1], 0 op_sel_hi:[1,0,0]
	v_pk_fma_f32 v[14:15], v[8:9], v[0:1], 0 op_sel_hi:[1,0,0]
	v_pk_fma_f32 v[24:25], v[10:11], v[4:5], 0 op_sel_hi:[1,0,0]
	v_pk_fma_f32 v[26:27], v[8:9], v[4:5], 0 op_sel_hi:[1,0,0]
	v_mul_f32_e32 v0, v65, v1
	v_mul_f32_e32 v4, v64, v5
	s_waitcnt vmcnt(6)
	v_pk_fma_f32 v[14:15], v[20:21], v[0:1], v[14:15] op_sel_hi:[1,0,1]
	v_pk_fma_f32 v[0:1], v[22:23], v[0:1], v[12:13] op_sel_hi:[1,0,1]
	v_pk_fma_f32 v[12:13], v[20:21], v[4:5], v[26:27] op_sel_hi:[1,0,1]
	v_pk_fma_f32 v[4:5], v[22:23], v[4:5], v[24:25] op_sel_hi:[1,0,1]
	v_or_b32_e32 v24, 0x100, v18
	v_ashrrev_i32_e32 v25, 31, v24
	v_lshlrev_b64 v[52:53], 2, v[24:25]
	v_lshl_add_u64 v[24:25], v[16:17], 0, v[52:53]
	s_waitcnt vmcnt(4)
	v_pk_fma_f32 v[0:1], v[94:95], v[2:3], v[0:1] op_sel_hi:[1,0,1]
	v_pk_fma_f32 v[14:15], v[92:93], v[2:3], v[14:15] op_sel_hi:[1,0,1]
	v_mul_f32_e32 v2, v65, v3
	v_pk_fma_f32 v[46:47], v[30:31], v[2:3], v[0:1] op_sel_hi:[1,0,1]
	v_or_b32_e32 v0, 0x200, v18
	v_ashrrev_i32_e32 v1, 31, v0
	v_lshlrev_b64 v[42:43], 2, v[0:1]
	v_lshl_add_u64 v[0:1], v[16:17], 0, v[42:43]
	v_pk_fma_f32 v[14:15], v[28:29], v[2:3], v[14:15] op_sel_hi:[1,0,1]
	v_pk_fma_f32 v[4:5], v[94:95], v[6:7], v[4:5] op_sel_hi:[1,0,1]
	v_pk_fma_f32 v[12:13], v[92:93], v[6:7], v[12:13] op_sel_hi:[1,0,1]
	v_mul_f32_e32 v6, v64, v7
	v_pk_fma_f32 v[4:5], v[30:31], v[6:7], v[4:5] op_sel_hi:[1,0,1]
	v_pk_fma_f32 v[12:13], v[28:29], v[6:7], v[12:13] op_sel_hi:[1,0,1]
	v_mul_f32_e32 v6, v65, v36
	v_mul_f32_e32 v36, v64, v33
	s_waitcnt vmcnt(3)
	v_pk_fma_f32 v[58:59], v[98:99], v[32:33], v[4:5] op_sel_hi:[1,0,1]
	v_or_b32_e32 v4, 0x280, v18
	v_ashrrev_i32_e32 v5, 31, v4
	v_pk_fma_f32 v[56:57], v[98:99], v[6:7], v[46:47] op_sel_hi:[1,0,1]
	v_lshlrev_b64 v[46:47], 2, v[4:5]
	v_lshl_add_u64 v[4:5], v[16:17], 0, v[46:47]
	v_pk_fma_f32 v[14:15], v[96:97], v[6:7], v[14:15] op_sel_hi:[1,0,1]
	v_pk_fma_f32 v[12:13], v[96:97], v[32:33], v[12:13] op_sel_hi:[1,0,1]
	v_mul_f32_e32 v32, v65, v37
	s_waitcnt vmcnt(2)
	v_pk_fma_f32 v[62:63], v[100:101], v[36:37], v[12:13] op_sel_hi:[1,0,1]
	v_or_b32_e32 v12, 0x300, v18
	v_ashrrev_i32_e32 v13, 31, v12
	v_pk_fma_f32 v[60:61], v[100:101], v[32:33], v[14:15] op_sel_hi:[1,0,1]
	v_pk_fma_f32 v[56:57], v[102:103], v[32:33], v[56:57] op_sel_hi:[1,0,1]
	v_lshlrev_b64 v[32:33], 2, v[12:13]
	v_lshl_add_u64 v[12:13], v[16:17], 0, v[32:33]
	v_or_b32_e32 v18, 0x380, v18
	v_pk_fma_f32 v[36:37], v[102:103], v[36:37], v[58:59] op_sel_hi:[1,0,1]
	v_ashrrev_i32_e32 v19, 31, v18
	s_waitcnt vmcnt(1)
	v_pk_fma_f32 v[58:59], v[106:107], v[34:35], v[36:37] op_sel_hi:[1,0,1]
	v_lshlrev_b64 v[36:37], 2, v[18:19]
	v_lshl_add_u64 v[16:17], v[16:17], 0, v[36:37]
	v_pk_fma_f32 v[56:57], v[106:107], v[38:39], v[56:57] op_sel_hi:[1,0,1]
	v_pk_fma_f32 v[60:61], v[104:105], v[38:39], v[60:61] op_sel_hi:[1,0,1]
	v_pk_fma_f32 v[62:63], v[104:105], v[34:35], v[62:63] op_sel_hi:[1,0,1]
	v_mul_f32_e32 v34, v65, v39
	v_mul_f32_e32 v38, v64, v35
	s_waitcnt vmcnt(0)
	v_pk_fma_f32 v[70:71], v[108:109], v[34:35], v[60:61] op_sel_hi:[1,0,1]
	v_pk_fma_f32 v[72:73], v[110:111], v[34:35], v[56:57] op_sel_hi:[1,0,1]
	v_mul_f32_e32 v34, 0x3fb8aa3b, v68
	v_pk_fma_f32 v[56:57], v[108:109], v[38:39], v[62:63] op_sel_hi:[1,0,1]
	v_pk_fma_f32 v[58:59], v[110:111], v[38:39], v[58:59] op_sel_hi:[1,0,1]
	v_fma_f32 v35, v68, s14, -v34
	v_rndne_f32_e32 v38, v34
	v_fmac_f32_e32 v35, 0x32a5705f, v68
	v_sub_f32_e32 v34, v34, v38
	v_add_f32_e32 v34, v34, v35
	v_exp_f32_e32 v34, v34
	v_cvt_i32_f32_e32 v35, v38
	s_mov_b32 s14, 0xc2ce8ed0
	v_cmp_ngt_f32_e32 vcc, s14, v68
	s_mov_b32 s14, 0x42b17218
	v_ldexp_f32 v34, v34, v35
	v_cndmask_b32_e32 v34, 0, v34, vcc
	v_cmp_nlt_f32_e32 vcc, s14, v68
	s_movk_i32 s14, 0x3e0
	v_mul_lo_u32 v35, v45, s14
	v_lshlrev_b32_e32 v38, 5, v66
	v_add3_u32 v35, v67, v35, v38
	ds_write_b128 v35, v[70:73] offset:2048
	ds_write_b128 v35, v[56:59] offset:2064
	v_add_u32_e32 v58, 0, v38
	s_waitcnt lgkmcnt(0)
	s_barrier
; #define LAS __attribute__((address_space(3)))
; DI void sample_item(LAS unsigned char* lds, const Args& a, int l, int item) {
;     ...
;     __syncthreads();
;     f32x4 kS = {0.f, 0.f, 0.f, 0.f}, qS = {0.f, 0.f, 0.f, 0.f};
; #pragma unroll
;     for (int g = 0; g < 16; ++g) { kS += *(const LAS f32x4*)(red + (g * 128 + dv4 * 4) * 2); qS += *(const LAS f32x4*)(red + (g * 128 + dv4 * 4) * 2 + 4); }
;     f32x4 v4 = *(const LAS f32x4*)(vals + 256 + dv4 * 4);
;     const f32x4 u = v4 * beta - kS * (beta * ga);
;     float* Sout = a.out + OUT_DS + (size_t)((l * 128 + b) * 4 + h) * 16384;
; #pragma unroll
;     for (int j = 0; j < 8; ++j) { const int dk = dkg * 8 + j; const float kk = vals[128 + dk] * ksc; __builtin_nontemporal_store(S[j] * ga + u * kk, (f32x4*)(Sout + dk * 128 + dv4 * 4)); }
	ds_read_b128 v[60:63], v58 offset:2048
	v_add_u32_e32 v35, 0, v128
	v_cndmask_b32_e32 v34, v165, v34, vcc
	v_mul_f32_e32 v68, v44, v34
	v_readlane_b32 s14, v254, 16
	s_waitcnt lgkmcnt(0)
	v_pk_add_f32 v[38:39], v[62:63], 0 op_sel_hi:[1,0]
	v_pk_add_f32 v[56:57], v[60:61], 0 op_sel_hi:[1,0]
	ds_read_b128 v[60:63], v58 offset:3072
	s_add_u32 s12, s14, s12
	v_readlane_b32 s14, v254, 17
	s_addc_u32 s13, s14, s13
	v_cmp_gt_u32_e32 vcc, 32, v41
	s_waitcnt lgkmcnt(0)
	v_pk_add_f32 v[38:39], v[38:39], v[62:63]
	v_pk_add_f32 v[56:57], v[56:57], v[60:61]
	ds_read_b128 v[60:63], v58 offset:4096
	s_waitcnt lgkmcnt(0)
	v_pk_add_f32 v[38:39], v[38:39], v[62:63]
	v_pk_add_f32 v[56:57], v[56:57], v[60:61]
	ds_read_b128 v[60:63], v58 offset:5120
	s_waitcnt lgkmcnt(0)
	v_pk_add_f32 v[38:39], v[38:39], v[62:63]
	v_pk_add_f32 v[56:57], v[56:57], v[60:61]
	ds_read_b128 v[60:63], v58 offset:6144
	s_waitcnt lgkmcnt(0)
	v_pk_add_f32 v[38:39], v[38:39], v[62:63]
	v_pk_add_f32 v[56:57], v[56:57], v[60:61]
	ds_read_b128 v[60:63], v58 offset:7168
	s_waitcnt lgkmcnt(0)
	v_pk_add_f32 v[38:39], v[38:39], v[62:63]
	v_pk_add_f32 v[56:57], v[56:57], v[60:61]
	ds_read_b128 v[60:63], v58 offset:8192
	s_waitcnt lgkmcnt(0)
	v_pk_add_f32 v[38:39], v[38:39], v[62:63]
	v_pk_add_f32 v[56:57], v[56:57], v[60:61]
	ds_read_b128 v[60:63], v58 offset:9216
	s_waitcnt lgkmcnt(0)
	v_pk_add_f32 v[38:39], v[38:39], v[62:63]
	v_pk_add_f32 v[56:57], v[56:57], v[60:61]
	ds_read_b128 v[60:63], v58 offset:10240
	s_waitcnt lgkmcnt(0)
	v_pk_add_f32 v[38:39], v[38:39], v[62:63]
	v_pk_add_f32 v[56:57], v[56:57], v[60:61]
	ds_read_b128 v[60:63], v58 offset:11264
	s_waitcnt lgkmcnt(0)
	v_pk_add_f32 v[38:39], v[38:39], v[62:63]
	v_pk_add_f32 v[56:57], v[56:57], v[60:61]
	ds_read_b128 v[60:63], v58 offset:12288
	s_waitcnt lgkmcnt(0)
	v_pk_add_f32 v[38:39], v[38:39], v[62:63]
	v_pk_add_f32 v[56:57], v[56:57], v[60:61]
	ds_read_b128 v[60:63], v58 offset:13312
	s_waitcnt lgkmcnt(0)
	v_pk_add_f32 v[38:39], v[38:39], v[62:63]
	v_pk_add_f32 v[56:57], v[56:57], v[60:61]
	ds_read_b128 v[60:63], v58 offset:14336
	s_waitcnt lgkmcnt(0)
	v_pk_add_f32 v[38:39], v[38:39], v[62:63]
	v_pk_add_f32 v[56:57], v[56:57], v[60:61]
	ds_read_b128 v[60:63], v58 offset:15360
	s_waitcnt lgkmcnt(0)
	v_pk_add_f32 v[38:39], v[38:39], v[62:63]
	v_pk_add_f32 v[56:57], v[56:57], v[60:61]
	ds_read_b128 v[60:63], v58 offset:16384
	s_waitcnt lgkmcnt(0)
	v_pk_add_f32 v[38:39], v[38:39], v[62:63]
	v_pk_add_f32 v[56:57], v[56:57], v[60:61]
	ds_read_b128 v[60:63], v58 offset:17408
	s_waitcnt lgkmcnt(0)
	v_pk_add_f32 v[38:39], v[38:39], v[62:63]
	v_pk_add_f32 v[56:57], v[56:57], v[60:61]
	ds_read_b128 v[60:63], v35 offset:1024
	v_pk_mul_f32 v[70:71], v[68:69], v[38:39] op_sel_hi:[0,1]
	v_pk_mul_f32 v[38:39], v[68:69], v[56:57] op_sel_hi:[0,1]
	v_lshl_add_u64 v[56:57], s[12:13], 0, v[128:129]
	v_lshl_add_u64 v[48:49], v[56:57], 0, v[48:49]
	s_waitcnt lgkmcnt(0)
	v_pk_fma_f32 v[38:39], v[44:45], v[60:61], v[38:39] op_sel_hi:[0,1,1] neg_lo:[0,0,1] neg_hi:[0,0,1]
	v_pk_fma_f32 v[44:45], v[44:45], v[62:63], v[70:71] op_sel_hi:[0,1,1] neg_lo:[0,0,1] neg_hi:[0,0,1]
	ds_read_b128 v[60:63], v67 offset:512
	s_waitcnt lgkmcnt(0)
	v_mul_f32_e32 v60, v65, v60
	v_pk_mul_f32 v[68:69], v[44:45], v[60:61] op_sel_hi:[1,0]
	v_pk_mul_f32 v[70:71], v[38:39], v[60:61] op_sel_hi:[1,0]
	v_pk_fma_f32 v[10:11], v[34:35], v[10:11], v[68:69] op_sel_hi:[0,1,1]
	v_pk_fma_f32 v[8:9], v[34:35], v[8:9], v[70:71] op_sel_hi:[0,1,1]
	global_store_dwordx4 v[48:49], v[8:11], off nt
	s_nop 1
	v_mul_f32_e32 v8, v65, v61
	v_pk_mul_f32 v[10:11], v[44:45], v[8:9] op_sel_hi:[1,0]
	v_pk_mul_f32 v[8:9], v[38:39], v[8:9] op_sel_hi:[1,0]
	v_pk_fma_f32 v[10:11], v[34:35], v[22:23], v[10:11] op_sel_hi:[0,1,1]
	v_pk_fma_f32 v[8:9], v[34:35], v[20:21], v[8:9] op_sel_hi:[0,1,1]
	v_lshl_add_u64 v[20:21], v[56:57], 0, v[50:51]
	global_store_dwordx4 v[20:21], v[8:11], off nt
	v_lshl_add_u64 v[20:21], v[56:57], 0, v[52:53]
	s_nop 0
	v_mul_f32_e32 v8, v65, v62
	v_pk_mul_f32 v[10:11], v[44:45], v[8:9] op_sel_hi:[1,0]
	v_pk_mul_f32 v[8:9], v[38:39], v[8:9] op_sel_hi:[1,0]
	v_pk_fma_f32 v[10:11], v[34:35], v[94:95], v[10:11] op_sel_hi:[0,1,1]
	v_pk_fma_f32 v[8:9], v[34:35], v[92:93], v[8:9] op_sel_hi:[0,1,1]
	global_store_dwordx4 v[20:21], v[8:11], off nt
	v_lshl_add_u64 v[20:21], v[56:57], 0, v[54:55]
	s_nop 0
	v_mul_f32_e32 v8, v65, v63
	v_pk_mul_f32 v[10:11], v[44:45], v[8:9] op_sel_hi:[1,0]
	v_pk_mul_f32 v[8:9], v[38:39], v[8:9] op_sel_hi:[1,0]
	v_pk_fma_f32 v[10:11], v[34:35], v[30:31], v[10:11] op_sel_hi:[0,1,1]
	v_pk_fma_f32 v[8:9], v[34:35], v[28:29], v[8:9] op_sel_hi:[0,1,1]
	global_store_dwordx4 v[20:21], v[8:11], off nt
	ds_read_b128 v[8:11], v67 offset:528
	s_waitcnt lgkmcnt(0)
	v_mul_f32_e32 v8, v65, v8
	v_pk_mul_f32 v[20:21], v[44:45], v[8:9] op_sel_hi:[1,0]
	v_pk_mul_f32 v[22:23], v[38:39], v[8:9] op_sel_hi:[1,0]
	v_pk_fma_f32 v[2:3], v[34:35], v[98:99], v[20:21] op_sel_hi:[0,1,1]
	v_pk_fma_f32 v[0:1], v[34:35], v[96:97], v[22:23] op_sel_hi:[0,1,1]
	v_lshl_add_u64 v[20:21], v[56:57], 0, v[42:43]
	global_store_dwordx4 v[20:21], v[0:3], off nt
	s_nop 1
	v_mul_f32_e32 v0, v65, v9
	v_pk_mul_f32 v[2:3], v[44:45], v[0:1] op_sel_hi:[1,0]
	v_pk_mul_f32 v[0:1], v[38:39], v[0:1] op_sel_hi:[1,0]
	v_pk_fma_f32 v[2:3], v[34:35], v[102:103], v[2:3] op_sel_hi:[0,1,1]
	v_pk_fma_f32 v[0:1], v[34:35], v[100:101], v[0:1] op_sel_hi:[0,1,1]
	v_lshl_add_u64 v[4:5], v[56:57], 0, v[46:47]
	global_store_dwordx4 v[4:5], v[0:3], off nt
	v_lshl_add_u64 v[4:5], v[56:57], 0, v[32:33]
	s_nop 0
	v_mul_f32_e32 v0, v65, v10
	v_pk_mul_f32 v[2:3], v[44:45], v[0:1] op_sel_hi:[1,0]
	v_pk_mul_f32 v[0:1], v[38:39], v[0:1] op_sel_hi:[1,0]
	v_pk_fma_f32 v[2:3], v[34:35], v[106:107], v[2:3] op_sel_hi:[0,1,1]
	v_pk_fma_f32 v[0:1], v[34:35], v[104:105], v[0:1] op_sel_hi:[0,1,1]
	global_store_dwordx4 v[4:5], v[0:3], off nt
	v_lshl_add_u64 v[4:5], v[56:57], 0, v[36:37]
	s_nop 0
	v_mul_f32_e32 v0, v65, v11
	v_pk_mul_f32 v[2:3], v[44:45], v[0:1] op_sel_hi:[1,0]
	v_pk_mul_f32 v[0:1], v[38:39], v[0:1] op_sel_hi:[1,0]
	v_pk_fma_f32 v[2:3], v[34:35], v[110:111], v[2:3] op_sel_hi:[0,1,1]
	v_pk_fma_f32 v[0:1], v[34:35], v[108:109], v[0:1] op_sel_hi:[0,1,1]
	global_store_dwordx4 v[4:5], v[0:3], off nt
	s_and_saveexec_b64 s[12:13], vcc
	s_cbranch_execz .LBB0_116
; #define LAS __attribute__((address_space(3)))
; DI void sample_item(LAS unsigned char* lds, const Args& a, int l, int item) {
;     ...
;     f32x4 kS = {0.f, 0.f, 0.f, 0.f}, qS = {0.f, 0.f, 0.f, 0.f};
; #pragma unroll
;     for (int g = 0; g < 16; ++g) { kS += *(const LAS f32x4*)(red + (g * 128 + dv4 * 4) * 2); qS += *(const LAS f32x4*)(red + (g * 128 + dv4 * 4) * 2 + 4); }
;     ...
;     if (dkg == 0) { const f32x4 o = qS * ga + u * qkdot; *(f32x4*)((float*)(a.ws + WS_O) + (size_t)row * 512 + h * 128 + dv4 * 4) = o; }
	v_lshlrev_b32_e32 v33, 2, v66
	ds_read_b128 v[0:3], v58 offset:2064
	ds_read_b128 v[4:7], v58 offset:3088
	ds_read_b128 v[8:11], v58 offset:4112
	ds_read_b128 v[12:15], v58 offset:5136
	ds_read_b128 v[16:19], v58 offset:6160
	ds_read_b128 v[20:23], v58 offset:7184
	ds_read_b128 v[24:27], v58 offset:8208
	ds_read_b128 v[28:31], v58 offset:9232
	ds_read_b128 v[46:49], v58 offset:10256
	ds_read_b128 v[50:53], v58 offset:11280
	ds_read_b128 v[54:57], v58 offset:12304
	ds_read_b128 v[60:63], v58 offset:13328
	ds_read_b128 v[66:69], v58 offset:14352
	ds_read_b128 v[70:73], v58 offset:15376
	ds_read_b128 v[74:77], v58 offset:16400
	ds_read_b128 v[78:81], v58 offset:17424
	s_waitcnt lgkmcnt(14)
	v_pk_add_f32 v[2:3], v[2:3], 0 op_sel_hi:[1,0]
	v_pk_add_f32 v[0:1], v[0:1], 0 op_sel_hi:[1,0]
	v_pk_add_f32 v[2:3], v[2:3], v[6:7]
	v_pk_add_f32 v[0:1], v[0:1], v[4:5]
	s_waitcnt lgkmcnt(13)
	v_pk_add_f32 v[2:3], v[2:3], v[10:11]
	v_pk_add_f32 v[0:1], v[0:1], v[8:9]
	s_waitcnt lgkmcnt(12)
	v_pk_add_f32 v[2:3], v[2:3], v[14:15]
	v_pk_add_f32 v[0:1], v[0:1], v[12:13]
	s_waitcnt lgkmcnt(11)
	v_pk_add_f32 v[2:3], v[2:3], v[18:19]
	v_pk_add_f32 v[0:1], v[0:1], v[16:17]
	s_waitcnt lgkmcnt(10)
	v_pk_add_f32 v[2:3], v[2:3], v[22:23]
	v_pk_add_f32 v[0:1], v[0:1], v[20:21]
	s_waitcnt lgkmcnt(9)
	v_pk_add_f32 v[2:3], v[2:3], v[26:27]
	v_pk_add_f32 v[0:1], v[0:1], v[24:25]
	s_waitcnt lgkmcnt(8)
	v_pk_add_f32 v[2:3], v[2:3], v[30:31]
	v_pk_add_f32 v[0:1], v[0:1], v[28:29]
	s_waitcnt lgkmcnt(7)
	v_pk_add_f32 v[2:3], v[2:3], v[48:49]
	v_pk_add_f32 v[0:1], v[0:1], v[46:47]
	s_waitcnt lgkmcnt(6)
	v_pk_add_f32 v[2:3], v[2:3], v[52:53]
	v_pk_add_f32 v[0:1], v[0:1], v[50:51]
	s_waitcnt lgkmcnt(5)
	v_pk_add_f32 v[2:3], v[2:3], v[56:57]
	v_pk_add_f32 v[0:1], v[0:1], v[54:55]
	s_waitcnt lgkmcnt(4)
	v_pk_add_f32 v[2:3], v[2:3], v[62:63]
	v_pk_add_f32 v[0:1], v[0:1], v[60:61]
	s_waitcnt lgkmcnt(3)
	v_pk_add_f32 v[2:3], v[2:3], v[68:69]
	v_pk_add_f32 v[0:1], v[0:1], v[66:67]
	s_lshl_b64 s[8:9], s[8:9], 11
	v_readlane_b32 s14, v253, 50
	v_mul_f32_e32 v32, v40, v64
	s_waitcnt lgkmcnt(2)
	v_pk_add_f32 v[2:3], v[2:3], v[72:73]
	v_pk_add_f32 v[0:1], v[0:1], v[70:71]
	v_readlane_b32 s15, v253, 51
	s_add_u32 s8, s14, s8
	v_mul_f32_e32 v32, v65, v32
	s_waitcnt lgkmcnt(1)
	v_pk_add_f32 v[2:3], v[2:3], v[76:77]
	v_pk_add_f32 v[0:1], v[0:1], v[74:75]
	s_addc_u32 s9, s15, s9
	s_lshl_b32 s14, s36, 9
	v_mov_b32_e32 v35, v34
	s_waitcnt lgkmcnt(0)
	v_pk_add_f32 v[2:3], v[2:3], v[80:81]
	v_pk_add_f32 v[0:1], v[0:1], v[78:79]
	v_pk_mul_f32 v[4:5], v[32:33], v[44:45] op_sel_hi:[0,1]
	v_pk_mul_f32 v[6:7], v[32:33], v[38:39] op_sel_hi:[0,1]
	v_mov_b32_e32 v8, v34
	v_mov_b32_e32 v9, v34
	s_add_u32 s8, s8, s14
	v_pk_fma_f32 v[2:3], v[8:9], v[2:3], v[4:5]
	v_pk_fma_f32 v[0:1], v[34:35], v[0:1], v[6:7]
	s_addc_u32 s9, s9, 0
	v_lshlrev_b32_e32 v4, 2, v33
	global_store_dwordx4 v4, v[0:3], s[8:9]
	s_branch .LBB0_116

; #define LAS __attribute__((address_space(3)))
; DI const float* INP(const Args& a, int i) { asm volatile("" : "+s"(i)); return a.in[i]; }
; DI void ln_phase(LAS unsigned char* lds, const Args& a, int l, int mode) {
;     int tid_ = threadIdx.x; asm volatile("" : "+v"(tid_));
;     const int tid = tid_, wave = tid >> 6, lane = tid & 63;
;     float* R = (float*)(a.ws + WS_R); bf16_t* XB = (bf16_t*)(a.ws + WS_XB);
;     const float* gam = INP(a, mode == 1 ? 5 : (mode == 2 ? 18 : 23)) + l * DM;
;     const float* bet = INP(a, mode == 1 ? 6 : (mode == 2 ? 19 : 24)) + l * DM;
;     LAS float* w8s = (LAS float*)lds;
;     if (mode == 1) { const float* win = INP(a, 10) + (size_t)l * DM * INDIM + 2048;
;         for (int i = tid; i < 8192; i += 512) { const int k = i >> 3, c = i & 7; w8s[c * 1024 + k] = win[(size_t)k * INDIM + c]; }
;         __syncthreads(); }
;     f32x4 g4[4], b4[4];
; #pragma unroll
;     for (int i = 0; i < 4; ++i) { g4[i] = *(const f32x4*)(gam + 256 * i + 4 * lane); b4[i] = *(const f32x4*)(bet + 256 * i + 4 * lane); }
;     float alog = 0.f, dtb = 0.f;
;     if (mode == 1) { alog = INP(a, 12)[l * 4 + (lane & 3)]; dtb = INP(a, 13)[l * 4 + (lane & 3)]; }
;     const bool wy = (mode == 3 && l == DEPTH - 1);
;     f32x4 xn[4];
;     { const int row = blockIdx.x * 8 + wave; if (row < ROWS) {
; #pragma unroll
;         for (int i = 0; i < 4; ++i) xn[i] = *(const f32x4*)(R + (size_t)row * DM + 256 * i + 4 * lane); } }
.LBB0_759:
	v_ashrrev_i32_e32 v32, 6, v32
	v_readlane_b32 s12, v254, 54
	s_nop 1
	v_add_u32_e32 v68, s12, v32
	v_cmp_gt_i32_e32 vcc, s59, v68
	s_and_saveexec_b64 s[94:95], vcc
	s_cbranch_execz .LBB0_783
	v_ashrrev_i32_e32 v69, 31, v68
	v_lshlrev_b32_e32 v33, 2, v64
	v_lshlrev_b64 v[36:37], 12, v[68:69]
	v_lshl_add_u64 v[36:37], s[68:69], 0, v[36:37]
	v_lshlrev_b32_e32 v66, 2, v33
	v_mov_b32_e32 v67, v129
	v_lshl_add_u64 v[36:37], v[36:37], 0, v[66:67]
	global_load_dwordx4 v[60:63], v[36:37], off
	global_load_dwordx4 v[56:59], v[36:37], off offset:1024
	global_load_dwordx4 v[52:55], v[36:37], off offset:2048
	global_load_dwordx4 v[48:51], v[36:37], off offset:3072
	v_lshlrev_b32_e32 v128, 1, v33
	v_and_b32_e32 v33, 64, v160
	v_add_u32_e32 v33, 64, v33
	v_xor_b32_e32 v35, 32, v160
	v_cmp_lt_i32_e32 vcc, v35, v33
	s_cmp_eq_u32 s2, 3
	s_cselect_b64 s[12:13], -1, 0
	v_cndmask_b32_e32 v35, v160, v35, vcc
	v_lshlrev_b32_e32 v85, 2, v35
	v_xor_b32_e32 v35, 16, v160
	v_cmp_lt_i32_e32 vcc, v35, v33
	s_sub_i32 s2, s62, 37
	s_cmp_lt_u32 s2, 12
	v_cndmask_b32_e32 v35, v160, v35, vcc
	v_lshlrev_b32_e32 v86, 2, v35
	v_xor_b32_e32 v35, 8, v160
	v_cmp_lt_i32_e32 vcc, v35, v33
	s_cselect_b64 s[14:15], -1, 0
	v_readlane_b32 s18, v254, 26
	v_cndmask_b32_e32 v35, v160, v35, vcc
	v_lshlrev_b32_e32 v87, 2, v35
	v_xor_b32_e32 v35, 4, v160
	v_cmp_lt_i32_e32 vcc, v35, v33
	s_and_b64 s[34:35], s[14:15], s[12:13]
	v_readlane_b32 s19, v254, 27
	v_cndmask_b32_e32 v35, v160, v35, vcc
	v_lshlrev_b32_e32 v88, 2, v35
	v_xor_b32_e32 v35, 2, v160
	v_cmp_lt_i32_e32 vcc, v35, v33
	s_and_b64 s[10:11], s[10:11], exec
	v_lshl_add_u64 v[70:71], s[68:69], 0, v[66:67]
	v_cndmask_b32_e32 v35, v160, v35, vcc
	v_lshlrev_b32_e32 v89, 2, v35
	v_xor_b32_e32 v35, 1, v160
	v_cmp_lt_i32_e32 vcc, v35, v33
	s_cselect_b32 s2, 4, 11
	v_lshl_add_u64 v[72:73], s[96:97], 0, v[128:129]
	v_cndmask_b32_e32 v33, v160, v35, vcc
	v_mov_b32_e32 v35, v129
	v_lshl_add_u64 v[74:75], s[18:19], 0, v[34:35]
	v_readlane_b32 s18, v254, 55
	v_lshlrev_b32_e32 v90, 2, v33
	v_cmp_gt_u32_e64 s[10:11], 4, v64
	v_cmp_eq_u32_e64 s[12:13], 0, v64
	v_cmp_eq_u32_e64 s[14:15], 1, v64
	v_cmp_eq_u32_e64 s[16:17], 2, v64
	v_add_u32_e32 v91, 0, v66
	v_add_u32_e32 v128, s18, v32
	s_mov_b64 s[28:29], 0
	s_waitcnt vmcnt(0)
	s_branch .LBB0_764

; DI void ln_phase(LAS unsigned char* lds, const Args& a, int l, int mode) {
;     ...
;     for (int row = blockIdx.x * 8 + wave; row < ROWS; row += gridDim.x * 8) {
;         float* rp = R + (size_t)row * DM;
;         f32x4 x[4];
; #pragma unroll
;         for (int i = 0; i < 4; ++i) x[i] = xn[i];
;         { const int nrow = row + gridDim.x * 8; if (nrow < ROWS) {
; #pragma unroll
;             for (int i = 0; i < 4; ++i) xn[i] = *(const f32x4*)(R + (size_t)nrow * DM + 256 * i + 4 * lane); } }
.LBB0_764:
	v_add_u32_e32 v76, s33, v68
	s_movk_i32 s25, 0x40ff
	v_cmp_gt_i32_e64 s[18:19], s59, v76
	v_cmp_lt_i32_e32 vcc, s25, v76
	v_mov_b32_e32 v32, v60
	v_mov_b32_e32 v33, v61
	v_mov_b32_e32 v34, v62
	v_mov_b32_e32 v35, v63
	v_mov_b32_e32 v36, v56
	v_mov_b32_e32 v37, v57
	v_mov_b32_e32 v38, v58
	v_mov_b32_e32 v39, v59
	v_mov_b32_e32 v40, v52
	v_mov_b32_e32 v41, v53
	v_mov_b32_e32 v42, v54
	v_mov_b32_e32 v43, v55
	v_mov_b32_e32 v44, v48
	v_mov_b32_e32 v45, v49
	v_mov_b32_e32 v46, v50
	v_mov_b32_e32 v47, v51
	s_and_saveexec_b64 s[36:37], s[18:19]
	s_cbranch_execz .LBB0_766
	v_ashrrev_i32_e32 v77, 31, v76
	v_lshlrev_b64 v[32:33], 12, v[76:77]
	v_lshl_add_u64 v[44:45], v[70:71], 0, v[32:33]
	global_load_dwordx4 v[32:35], v[44:45], off
	global_load_dwordx4 v[36:39], v[44:45], off offset:1024
	global_load_dwordx4 v[40:43], v[44:45], off offset:2048
	s_nop 0
	global_load_dwordx4 v[44:47], v[44:45], off offset:3072

; DI const float* INP(const Args& a, int i) { asm volatile("" : "+s"(i)); return a.in[i]; }
; DI unsigned pk2(float a, float b) { f32x2 v = {a, b}; nbf2 r = __builtin_convertvector(v, nbf2); return __builtin_bit_cast(unsigned, r); }
; DI bf16_t f2bf(float a) { return (bf16_t)(pk2(a, 0.f) & 0xffffu); }
; DI void prep_phase(LAS unsigned char* lds, const Args& a) {
;     ...
;     const size_t gt = (size_t)blockIdx.x * 512 + tid, gs = (size_t)gridDim.x * 512;
;     for (size_t i = gt; i < (size_t)DEPTH * 4 * 128 * 128; i += gs) { const int d = (int)(i & 127), cc = (int)((i >> 7) & 127); const size_t lg = i >> 14; const int l = (int)(lg >> 2), g = (int)(lg & 3);
;         ((bf16_t*)(a.ws + WS_W + (size_t)l * W_LSTRIDE + WO_PW))[(size_t)(g * 128 + d) * 128 + cc] = f2bf(INP(a, 15)[i]); }
;     { float* R = (float*)(a.ws + WS_R); bf16_t* XB = (bf16_t*)(a.ws + WS_XB);
;       for (size_t i = gt; i < (size_t)ROWS * 256; i += gs) { const size_t row = i >> 8; const int c4 = (int)(i & 255) * 4; f32x4 v = {0.f, 0.f, 0.f, 0.f};
;           if (row < NPROMPT) v = *(const f32x4*)(INP(a, 0) + row * DM + c4); else if (row < NVALID) v = *(const f32x4*)(INP(a, 1) + (row - NPROMPT) * DM + c4);
;           *(f32x4*)(R + row * DM + c4) = v * ALPHA; u32x2 w; w.x = pk2(v[0], v[1]); w.y = pk2(v[2], v[3]); *(u32x2*)(XB + row * DM + c4) = w; } }
.LBB0_868:
	s_or_b64 exec, exec, s[10:11]
	s_load_dwordx2 s[8:9], s[0:1], 0x0
	v_lshlrev_b64 v[54:55], 4, v[4:5]
	v_lshlrev_b64 v[58:59], 3, v[4:5]
	v_lshl_add_u64 v[56:57], s[68:69], 0, v[54:55]
	v_lshl_add_u64 v[58:59], s[96:97], 0, v[58:59]
	s_mov_b64 s[12:13], 0x200000
	s_mov_b64 s[14:15], 0x100000
	s_waitcnt lgkmcnt(0)
	v_lshl_add_u64 v[54:55], s[8:9], 0, v[54:55]
	global_load_dwordx4 v[16:19], v[54:55], off
	v_lshl_add_u64 v[54:55], v[54:55], 0, s[12:13]
	global_load_dwordx4 v[20:23], v[54:55], off
	v_lshl_add_u64 v[54:55], v[54:55], 0, s[12:13]
	global_load_dwordx4 v[24:27], v[54:55], off
	v_lshl_add_u64 v[54:55], v[54:55], 0, s[12:13]
	global_load_dwordx4 v[28:31], v[54:55], off
	v_lshl_add_u64 v[54:55], v[54:55], 0, s[12:13]
	global_load_dwordx4 v[32:35], v[54:55], off
	v_lshl_add_u64 v[54:55], v[54:55], 0, s[12:13]
	global_load_dwordx4 v[36:39], v[54:55], off
	v_lshl_add_u64 v[54:55], v[54:55], 0, s[12:13]
	global_load_dwordx4 v[40:43], v[54:55], off
	v_lshl_add_u64 v[54:55], v[54:55], 0, s[12:13]
	global_load_dwordx4 v[44:47], v[54:55], off
	v_lshl_add_u64 v[54:55], v[54:55], 0, s[12:13]
	global_load_dwordx4 v[66:69], v[54:55], off
	v_lshl_add_u64 v[54:55], v[54:55], 0, s[12:13]
	global_load_dwordx4 v[70:73], v[54:55], off
	v_lshl_add_u64 v[54:55], v[54:55], 0, s[12:13]
	global_load_dwordx4 v[74:77], v[54:55], off
	v_lshl_add_u64 v[54:55], v[54:55], 0, s[12:13]
	global_load_dwordx4 v[78:81], v[54:55], off
	v_lshl_add_u64 v[54:55], v[54:55], 0, s[12:13]
	global_load_dwordx4 v[82:85], v[54:55], off
	v_lshl_add_u64 v[54:55], v[54:55], 0, s[12:13]
	global_load_dwordx4 v[86:89], v[54:55], off
	v_lshl_add_u64 v[54:55], v[54:55], 0, s[12:13]
	global_load_dwordx4 v[90:93], v[54:55], off
	v_lshl_add_u64 v[54:55], v[54:55], 0, s[12:13]
	global_load_dwordx4 v[94:97], v[54:55], off
	v_lshl_add_u64 v[54:55], v[54:55], 0, s[12:13]
	s_waitcnt vmcnt(15)
	v_pk_mul_f32 v[48:49], v[16:17], s[90:91] op_sel_hi:[1,0]
	v_pk_mul_f32 v[50:51], v[18:19], s[90:91] op_sel_hi:[1,0]
	v_cvt_pk_bf16_f32 v52, v16, v17
	v_cvt_pk_bf16_f32 v53, v18, v19
	global_store_dwordx4 v[56:57], v[48:51], off
	global_store_dwordx2 v[58:59], v[52:53], off
	v_lshl_add_u64 v[56:57], v[56:57], 0, s[12:13]
	v_lshl_add_u64 v[58:59], v[58:59], 0, s[14:15]
	s_waitcnt vmcnt(16)
	v_pk_mul_f32 v[60:61], v[20:21], s[90:91] op_sel_hi:[1,0]
	v_pk_mul_f32 v[62:63], v[22:23], s[90:91] op_sel_hi:[1,0]
	v_cvt_pk_bf16_f32 v64, v20, v21
	v_cvt_pk_bf16_f32 v65, v22, v23
	global_store_dwordx4 v[56:57], v[60:63], off
	global_store_dwordx2 v[58:59], v[64:65], off
	v_lshl_add_u64 v[56:57], v[56:57], 0, s[12:13]
	v_lshl_add_u64 v[58:59], v[58:59], 0, s[14:15]
	s_waitcnt vmcnt(17)
	v_pk_mul_f32 v[48:49], v[24:25], s[90:91] op_sel_hi:[1,0]
	v_pk_mul_f32 v[50:51], v[26:27], s[90:91] op_sel_hi:[1,0]
	v_cvt_pk_bf16_f32 v52, v24, v25
	v_cvt_pk_bf16_f32 v53, v26, v27
	global_store_dwordx4 v[56:57], v[48:51], off
	global_store_dwordx2 v[58:59], v[52:53], off
	v_lshl_add_u64 v[56:57], v[56:57], 0, s[12:13]
	v_lshl_add_u64 v[58:59], v[58:59], 0, s[14:15]
	s_waitcnt vmcnt(18)
	v_pk_mul_f32 v[60:61], v[28:29], s[90:91] op_sel_hi:[1,0]
	v_pk_mul_f32 v[62:63], v[30:31], s[90:91] op_sel_hi:[1,0]
	v_cvt_pk_bf16_f32 v64, v28, v29
	v_cvt_pk_bf16_f32 v65, v30, v31
	global_store_dwordx4 v[56:57], v[60:63], off
	global_store_dwordx2 v[58:59], v[64:65], off
	v_lshl_add_u64 v[56:57], v[56:57], 0, s[12:13]
	v_lshl_add_u64 v[58:59], v[58:59], 0, s[14:15]
	s_waitcnt vmcnt(19)
	v_pk_mul_f32 v[48:49], v[32:33], s[90:91] op_sel_hi:[1,0]
	v_pk_mul_f32 v[50:51], v[34:35], s[90:91] op_sel_hi:[1,0]
	v_cvt_pk_bf16_f32 v52, v32, v33
	v_cvt_pk_bf16_f32 v53, v34, v35
	global_store_dwordx4 v[56:57], v[48:51], off
	global_store_dwordx2 v[58:59], v[52:53], off
	v_lshl_add_u64 v[56:57], v[56:57], 0, s[12:13]
	v_lshl_add_u64 v[58:59], v[58:59], 0, s[14:15]
	s_waitcnt vmcnt(20)
	v_pk_mul_f32 v[60:61], v[36:37], s[90:91] op_sel_hi:[1,0]
	v_pk_mul_f32 v[62:63], v[38:39], s[90:91] op_sel_hi:[1,0]
	v_cvt_pk_bf16_f32 v64, v36, v37
	v_cvt_pk_bf16_f32 v65, v38, v39
	global_store_dwordx4 v[56:57], v[60:63], off
	global_store_dwordx2 v[58:59], v[64:65], off
	v_lshl_add_u64 v[56:57], v[56:57], 0, s[12:13]
	v_lshl_add_u64 v[58:59], v[58:59], 0, s[14:15]
	s_waitcnt vmcnt(21)
	v_pk_mul_f32 v[48:49], v[40:41], s[90:91] op_sel_hi:[1,0]
	v_pk_mul_f32 v[50:51], v[42:43], s[90:91] op_sel_hi:[1,0]
	v_cvt_pk_bf16_f32 v52, v40, v41
	v_cvt_pk_bf16_f32 v53, v42, v43
	global_store_dwordx4 v[56:57], v[48:51], off
	global_store_dwordx2 v[58:59], v[52:53], off
	v_lshl_add_u64 v[56:57], v[56:57], 0, s[12:13]
	v_lshl_add_u64 v[58:59], v[58:59], 0, s[14:15]
	s_waitcnt vmcnt(22)
	v_pk_mul_f32 v[60:61], v[44:45], s[90:91] op_sel_hi:[1,0]
	v_pk_mul_f32 v[62:63], v[46:47], s[90:91] op_sel_hi:[1,0]
	v_cvt_pk_bf16_f32 v64, v44, v45
	v_cvt_pk_bf16_f32 v65, v46, v47
	global_store_dwordx4 v[56:57], v[60:63], off
	global_store_dwordx2 v[58:59], v[64:65], off
	v_lshl_add_u64 v[56:57], v[56:57], 0, s[12:13]
	v_lshl_add_u64 v[58:59], v[58:59], 0, s[14:15]
	global_load_dwordx4 v[16:19], v[54:55], off
	v_lshl_add_u64 v[54:55], v[54:55], 0, s[12:13]
	global_load_dwordx4 v[20:23], v[54:55], off
	v_lshl_add_u64 v[54:55], v[54:55], 0, s[12:13]
	global_load_dwordx4 v[24:27], v[54:55], off
	v_lshl_add_u64 v[54:55], v[54:55], 0, s[12:13]
	global_load_dwordx4 v[28:31], v[54:55], off
	v_lshl_add_u64 v[54:55], v[54:55], 0, s[12:13]
	global_load_dwordx4 v[32:35], v[54:55], off
	v_lshl_add_u64 v[54:55], v[54:55], 0, s[12:13]
	global_load_dwordx4 v[36:39], v[54:55], off
	v_lshl_add_u64 v[54:55], v[54:55], 0, s[12:13]
	global_load_dwordx4 v[40:43], v[54:55], off
	v_lshl_add_u64 v[54:55], v[54:55], 0, s[12:13]
	global_load_dwordx4 v[44:47], v[54:55], off
	v_lshl_add_u64 v[54:55], v[54:55], 0, s[12:13]
	s_waitcnt vmcnt(31)
; DI const float* INP(const Args& a, int i) { asm volatile("" : "+s"(i)); return a.in[i]; }
; DI unsigned pk2(float a, float b) { f32x2 v = {a, b}; nbf2 r = __builtin_convertvector(v, nbf2); return __builtin_bit_cast(unsigned, r); }
; DI bf16_t f2bf(float a) { return (bf16_t)(pk2(a, 0.f) & 0xffffu); }
; DI void prep_phase(LAS unsigned char* lds, const Args& a) {
;     ...
;     const size_t gt = (size_t)blockIdx.x * 512 + tid, gs = (size_t)gridDim.x * 512;
;     for (size_t i = gt; i < (size_t)DEPTH * 4 * 128 * 128; i += gs) { const int d = (int)(i & 127), cc = (int)((i >> 7) & 127); const size_t lg = i >> 14; const int l = (int)(lg >> 2), g = (int)(lg & 3);
;         ((bf16_t*)(a.ws + WS_W + (size_t)l * W_LSTRIDE + WO_PW))[(size_t)(g * 128 + d) * 128 + cc] = f2bf(INP(a, 15)[i]); }
;     { float* R = (float*)(a.ws + WS_R); bf16_t* XB = (bf16_t*)(a.ws + WS_XB);
;       for (size_t i = gt; i < (size_t)ROWS * 256; i += gs) { const size_t row = i >> 8; const int c4 = (int)(i & 255) * 4; f32x4 v = {0.f, 0.f, 0.f, 0.f};
;           if (row < NPROMPT) v = *(const f32x4*)(INP(a, 0) + row * DM + c4); else if (row < NVALID) v = *(const f32x4*)(INP(a, 1) + (row - NPROMPT) * DM + c4);
;           *(f32x4*)(R + row * DM + c4) = v * ALPHA; u32x2 w; w.x = pk2(v[0], v[1]); w.y = pk2(v[2], v[3]); *(u32x2*)(XB + row * DM + c4) = w; } }
	v_pk_mul_f32 v[48:49], v[66:67], s[90:91] op_sel_hi:[1,0]
	v_pk_mul_f32 v[50:51], v[68:69], s[90:91] op_sel_hi:[1,0]
	v_cvt_pk_bf16_f32 v52, v66, v67
	v_cvt_pk_bf16_f32 v53, v68, v69
	global_store_dwordx4 v[56:57], v[48:51], off
	global_store_dwordx2 v[58:59], v[52:53], off
	v_lshl_add_u64 v[56:57], v[56:57], 0, s[12:13]
	v_lshl_add_u64 v[58:59], v[58:59], 0, s[14:15]
	s_waitcnt vmcnt(32)
	v_pk_mul_f32 v[60:61], v[70:71], s[90:91] op_sel_hi:[1,0]
	v_pk_mul_f32 v[62:63], v[72:73], s[90:91] op_sel_hi:[1,0]
	v_cvt_pk_bf16_f32 v64, v70, v71
	v_cvt_pk_bf16_f32 v65, v72, v73
	global_store_dwordx4 v[56:57], v[60:63], off
	global_store_dwordx2 v[58:59], v[64:65], off
	v_lshl_add_u64 v[56:57], v[56:57], 0, s[12:13]
	v_lshl_add_u64 v[58:59], v[58:59], 0, s[14:15]
	s_waitcnt vmcnt(33)
	v_pk_mul_f32 v[48:49], v[74:75], s[90:91] op_sel_hi:[1,0]
	v_pk_mul_f32 v[50:51], v[76:77], s[90:91] op_sel_hi:[1,0]
	v_cvt_pk_bf16_f32 v52, v74, v75
	v_cvt_pk_bf16_f32 v53, v76, v77
	global_store_dwordx4 v[56:57], v[48:51], off
	global_store_dwordx2 v[58:59], v[52:53], off
	v_lshl_add_u64 v[56:57], v[56:57], 0, s[12:13]
	v_lshl_add_u64 v[58:59], v[58:59], 0, s[14:15]
	s_waitcnt vmcnt(34)
	v_pk_mul_f32 v[60:61], v[78:79], s[90:91] op_sel_hi:[1,0]
	v_pk_mul_f32 v[62:63], v[80:81], s[90:91] op_sel_hi:[1,0]
	v_cvt_pk_bf16_f32 v64, v78, v79
	v_cvt_pk_bf16_f32 v65, v80, v81
	global_store_dwordx4 v[56:57], v[60:63], off
	global_store_dwordx2 v[58:59], v[64:65], off
	v_lshl_add_u64 v[56:57], v[56:57], 0, s[12:13]
	v_lshl_add_u64 v[58:59], v[58:59], 0, s[14:15]
	s_waitcnt vmcnt(35)
	v_pk_mul_f32 v[48:49], v[82:83], s[90:91] op_sel_hi:[1,0]
	v_pk_mul_f32 v[50:51], v[84:85], s[90:91] op_sel_hi:[1,0]
	v_cvt_pk_bf16_f32 v52, v82, v83
	v_cvt_pk_bf16_f32 v53, v84, v85
	global_store_dwordx4 v[56:57], v[48:51], off
	global_store_dwordx2 v[58:59], v[52:53], off
	v_lshl_add_u64 v[56:57], v[56:57], 0, s[12:13]
	v_lshl_add_u64 v[58:59], v[58:59], 0, s[14:15]
	s_waitcnt vmcnt(36)
	v_pk_mul_f32 v[60:61], v[86:87], s[90:91] op_sel_hi:[1,0]
	v_pk_mul_f32 v[62:63], v[88:89], s[90:91] op_sel_hi:[1,0]
	v_cvt_pk_bf16_f32 v64, v86, v87
	v_cvt_pk_bf16_f32 v65, v88, v89
	global_store_dwordx4 v[56:57], v[60:63], off
	global_store_dwordx2 v[58:59], v[64:65], off
	v_lshl_add_u64 v[56:57], v[56:57], 0, s[12:13]
	v_lshl_add_u64 v[58:59], v[58:59], 0, s[14:15]
	s_waitcnt vmcnt(37)
	v_pk_mul_f32 v[48:49], v[90:91], s[90:91] op_sel_hi:[1,0]
	v_pk_mul_f32 v[50:51], v[92:93], s[90:91] op_sel_hi:[1,0]
	v_cvt_pk_bf16_f32 v52, v90, v91
	v_cvt_pk_bf16_f32 v53, v92, v93
	global_store_dwordx4 v[56:57], v[48:51], off
	global_store_dwordx2 v[58:59], v[52:53], off
	v_lshl_add_u64 v[56:57], v[56:57], 0, s[12:13]
	v_lshl_add_u64 v[58:59], v[58:59], 0, s[14:15]
	s_waitcnt vmcnt(38)
	v_pk_mul_f32 v[60:61], v[94:95], s[90:91] op_sel_hi:[1,0]
	v_pk_mul_f32 v[62:63], v[96:97], s[90:91] op_sel_hi:[1,0]
	v_cvt_pk_bf16_f32 v64, v94, v95
	v_cvt_pk_bf16_f32 v65, v96, v97
	global_store_dwordx4 v[56:57], v[60:63], off
	global_store_dwordx2 v[58:59], v[64:65], off
	v_lshl_add_u64 v[56:57], v[56:57], 0, s[12:13]
	v_lshl_add_u64 v[58:59], v[58:59], 0, s[14:15]
	global_load_dwordx4 v[66:69], v[54:55], off
	v_lshl_add_u64 v[54:55], v[54:55], 0, s[12:13]
	global_load_dwordx4 v[70:73], v[54:55], off
	v_lshl_add_u64 v[54:55], v[54:55], 0, s[12:13]
	global_load_dwordx4 v[74:77], v[54:55], off
	v_lshl_add_u64 v[54:55], v[54:55], 0, s[12:13]
	global_load_dwordx4 v[78:81], v[54:55], off
	v_lshl_add_u64 v[54:55], v[54:55], 0, s[12:13]
	global_load_dwordx4 v[82:85], v[54:55], off
	v_lshl_add_u64 v[54:55], v[54:55], 0, s[12:13]
	global_load_dwordx4 v[86:89], v[54:55], off
	v_lshl_add_u64 v[54:55], v[54:55], 0, s[12:13]
	global_load_dwordx4 v[90:93], v[54:55], off
	v_lshl_add_u64 v[54:55], v[54:55], 0, s[12:13]
	global_load_dwordx4 v[94:97], v[54:55], off
	v_lshl_add_u64 v[54:55], v[54:55], 0, s[12:13]
	s_waitcnt vmcnt(31)
	v_pk_mul_f32 v[48:49], v[16:17], s[90:91] op_sel_hi:[1,0]
	v_pk_mul_f32 v[50:51], v[18:19], s[90:91] op_sel_hi:[1,0]
	v_cvt_pk_bf16_f32 v52, v16, v17
	v_cvt_pk_bf16_f32 v53, v18, v19
	global_store_dwordx4 v[56:57], v[48:51], off
	global_store_dwordx2 v[58:59], v[52:53], off
	v_lshl_add_u64 v[56:57], v[56:57], 0, s[12:13]
	v_lshl_add_u64 v[58:59], v[58:59], 0, s[14:15]
	s_waitcnt vmcnt(32)
	v_pk_mul_f32 v[60:61], v[20:21], s[90:91] op_sel_hi:[1,0]
	v_pk_mul_f32 v[62:63], v[22:23], s[90:91] op_sel_hi:[1,0]
	v_cvt_pk_bf16_f32 v64, v20, v21
	v_cvt_pk_bf16_f32 v65, v22, v23
	global_store_dwordx4 v[56:57], v[60:63], off
	global_store_dwordx2 v[58:59], v[64:65], off
	v_lshl_add_u64 v[56:57], v[56:57], 0, s[12:13]
	v_lshl_add_u64 v[58:59], v[58:59], 0, s[14:15]
	s_waitcnt vmcnt(33)
	v_pk_mul_f32 v[48:49], v[24:25], s[90:91] op_sel_hi:[1,0]
	v_pk_mul_f32 v[50:51], v[26:27], s[90:91] op_sel_hi:[1,0]
	v_cvt_pk_bf16_f32 v52, v24, v25
	v_cvt_pk_bf16_f32 v53, v26, v27
	global_store_dwordx4 v[56:57], v[48:51], off
	global_store_dwordx2 v[58:59], v[52:53], off
	v_lshl_add_u64 v[56:57], v[56:57], 0, s[12:13]
	v_lshl_add_u64 v[58:59], v[58:59], 0, s[14:15]
	s_waitcnt vmcnt(34)
; DI const float* INP(const Args& a, int i) { asm volatile("" : "+s"(i)); return a.in[i]; }
; DI unsigned pk2(float a, float b) { f32x2 v = {a, b}; nbf2 r = __builtin_convertvector(v, nbf2); return __builtin_bit_cast(unsigned, r); }
; DI bf16_t f2bf(float a) { return (bf16_t)(pk2(a, 0.f) & 0xffffu); }
; DI void prep_phase(LAS unsigned char* lds, const Args& a) {
;     ...
;     const size_t gt = (size_t)blockIdx.x * 512 + tid, gs = (size_t)gridDim.x * 512;
;     for (size_t i = gt; i < (size_t)DEPTH * 4 * 128 * 128; i += gs) { const int d = (int)(i & 127), cc = (int)((i >> 7) & 127); const size_t lg = i >> 14; const int l = (int)(lg >> 2), g = (int)(lg & 3);
;         ((bf16_t*)(a.ws + WS_W + (size_t)l * W_LSTRIDE + WO_PW))[(size_t)(g * 128 + d) * 128 + cc] = f2bf(INP(a, 15)[i]); }
;     { float* R = (float*)(a.ws + WS_R); bf16_t* XB = (bf16_t*)(a.ws + WS_XB);
;       for (size_t i = gt; i < (size_t)ROWS * 256; i += gs) { const size_t row = i >> 8; const int c4 = (int)(i & 255) * 4; f32x4 v = {0.f, 0.f, 0.f, 0.f};
;           if (row < NPROMPT) v = *(const f32x4*)(INP(a, 0) + row * DM + c4); else if (row < NVALID) v = *(const f32x4*)(INP(a, 1) + (row - NPROMPT) * DM + c4);
;           *(f32x4*)(R + row * DM + c4) = v * ALPHA; u32x2 w; w.x = pk2(v[0], v[1]); w.y = pk2(v[2], v[3]); *(u32x2*)(XB + row * DM + c4) = w; } }
	v_pk_mul_f32 v[60:61], v[28:29], s[90:91] op_sel_hi:[1,0]
	v_pk_mul_f32 v[62:63], v[30:31], s[90:91] op_sel_hi:[1,0]
	v_cvt_pk_bf16_f32 v64, v28, v29
	v_cvt_pk_bf16_f32 v65, v30, v31
	global_store_dwordx4 v[56:57], v[60:63], off
	global_store_dwordx2 v[58:59], v[64:65], off
	v_lshl_add_u64 v[56:57], v[56:57], 0, s[12:13]
	v_lshl_add_u64 v[58:59], v[58:59], 0, s[14:15]
	s_waitcnt vmcnt(35)
	v_pk_mul_f32 v[48:49], v[32:33], s[90:91] op_sel_hi:[1,0]
	v_pk_mul_f32 v[50:51], v[34:35], s[90:91] op_sel_hi:[1,0]
	v_cvt_pk_bf16_f32 v52, v32, v33
	v_cvt_pk_bf16_f32 v53, v34, v35
	global_store_dwordx4 v[56:57], v[48:51], off
	global_store_dwordx2 v[58:59], v[52:53], off
	v_lshl_add_u64 v[56:57], v[56:57], 0, s[12:13]
	v_lshl_add_u64 v[58:59], v[58:59], 0, s[14:15]
	s_waitcnt vmcnt(36)
	v_pk_mul_f32 v[60:61], v[36:37], s[90:91] op_sel_hi:[1,0]
	v_pk_mul_f32 v[62:63], v[38:39], s[90:91] op_sel_hi:[1,0]
	v_cvt_pk_bf16_f32 v64, v36, v37
	v_cvt_pk_bf16_f32 v65, v38, v39
	global_store_dwordx4 v[56:57], v[60:63], off
	global_store_dwordx2 v[58:59], v[64:65], off
	v_lshl_add_u64 v[56:57], v[56:57], 0, s[12:13]
	v_lshl_add_u64 v[58:59], v[58:59], 0, s[14:15]
	s_waitcnt vmcnt(37)
	v_pk_mul_f32 v[48:49], v[40:41], s[90:91] op_sel_hi:[1,0]
	v_pk_mul_f32 v[50:51], v[42:43], s[90:91] op_sel_hi:[1,0]
	v_cvt_pk_bf16_f32 v52, v40, v41
	v_cvt_pk_bf16_f32 v53, v42, v43
	global_store_dwordx4 v[56:57], v[48:51], off
	global_store_dwordx2 v[58:59], v[52:53], off
	v_lshl_add_u64 v[56:57], v[56:57], 0, s[12:13]
	v_lshl_add_u64 v[58:59], v[58:59], 0, s[14:15]
	s_waitcnt vmcnt(38)
	v_pk_mul_f32 v[60:61], v[44:45], s[90:91] op_sel_hi:[1,0]
	v_pk_mul_f32 v[62:63], v[46:47], s[90:91] op_sel_hi:[1,0]
	v_cvt_pk_bf16_f32 v64, v44, v45
	v_cvt_pk_bf16_f32 v65, v46, v47
	global_store_dwordx4 v[56:57], v[60:63], off
	global_store_dwordx2 v[58:59], v[64:65], off
	v_lshl_add_u64 v[56:57], v[56:57], 0, s[12:13]
	v_lshl_add_u64 v[58:59], v[58:59], 0, s[14:15]
	s_waitcnt vmcnt(23)
	v_pk_mul_f32 v[48:49], v[66:67], s[90:91] op_sel_hi:[1,0]
	v_pk_mul_f32 v[50:51], v[68:69], s[90:91] op_sel_hi:[1,0]
	v_cvt_pk_bf16_f32 v52, v66, v67
	v_cvt_pk_bf16_f32 v53, v68, v69
	global_store_dwordx4 v[56:57], v[48:51], off
	global_store_dwordx2 v[58:59], v[52:53], off
	v_lshl_add_u64 v[56:57], v[56:57], 0, s[12:13]
	v_lshl_add_u64 v[58:59], v[58:59], 0, s[14:15]
	s_waitcnt vmcnt(24)
	v_pk_mul_f32 v[60:61], v[70:71], s[90:91] op_sel_hi:[1,0]
	v_pk_mul_f32 v[62:63], v[72:73], s[90:91] op_sel_hi:[1,0]
	v_cvt_pk_bf16_f32 v64, v70, v71
	v_cvt_pk_bf16_f32 v65, v72, v73
	global_store_dwordx4 v[56:57], v[60:63], off
	global_store_dwordx2 v[58:59], v[64:65], off
	v_lshl_add_u64 v[56:57], v[56:57], 0, s[12:13]
	v_lshl_add_u64 v[58:59], v[58:59], 0, s[14:15]
	s_waitcnt vmcnt(25)
	v_pk_mul_f32 v[48:49], v[74:75], s[90:91] op_sel_hi:[1,0]
	v_pk_mul_f32 v[50:51], v[76:77], s[90:91] op_sel_hi:[1,0]
	v_cvt_pk_bf16_f32 v52, v74, v75
	v_cvt_pk_bf16_f32 v53, v76, v77
	global_store_dwordx4 v[56:57], v[48:51], off
	global_store_dwordx2 v[58:59], v[52:53], off
	v_lshl_add_u64 v[56:57], v[56:57], 0, s[12:13]
	v_lshl_add_u64 v[58:59], v[58:59], 0, s[14:15]
	s_waitcnt vmcnt(26)
	v_pk_mul_f32 v[60:61], v[78:79], s[90:91] op_sel_hi:[1,0]
	v_pk_mul_f32 v[62:63], v[80:81], s[90:91] op_sel_hi:[1,0]
	v_cvt_pk_bf16_f32 v64, v78, v79
	v_cvt_pk_bf16_f32 v65, v80, v81
	global_store_dwordx4 v[56:57], v[60:63], off
	global_store_dwordx2 v[58:59], v[64:65], off
	v_lshl_add_u64 v[56:57], v[56:57], 0, s[12:13]
	v_lshl_add_u64 v[58:59], v[58:59], 0, s[14:15]
	s_waitcnt vmcnt(27)
	v_pk_mul_f32 v[48:49], v[82:83], s[90:91] op_sel_hi:[1,0]
	v_pk_mul_f32 v[50:51], v[84:85], s[90:91] op_sel_hi:[1,0]
	v_cvt_pk_bf16_f32 v52, v82, v83
	v_cvt_pk_bf16_f32 v53, v84, v85
	global_store_dwordx4 v[56:57], v[48:51], off
	global_store_dwordx2 v[58:59], v[52:53], off
	v_lshl_add_u64 v[56:57], v[56:57], 0, s[12:13]
	v_lshl_add_u64 v[58:59], v[58:59], 0, s[14:15]
	s_waitcnt vmcnt(28)
	v_pk_mul_f32 v[60:61], v[86:87], s[90:91] op_sel_hi:[1,0]
	v_pk_mul_f32 v[62:63], v[88:89], s[90:91] op_sel_hi:[1,0]
	v_cvt_pk_bf16_f32 v64, v86, v87
	v_cvt_pk_bf16_f32 v65, v88, v89
	global_store_dwordx4 v[56:57], v[60:63], off
	global_store_dwordx2 v[58:59], v[64:65], off
	v_lshl_add_u64 v[56:57], v[56:57], 0, s[12:13]
	v_lshl_add_u64 v[58:59], v[58:59], 0, s[14:15]
	s_waitcnt vmcnt(29)
	v_pk_mul_f32 v[48:49], v[90:91], s[90:91] op_sel_hi:[1,0]
	v_pk_mul_f32 v[50:51], v[92:93], s[90:91] op_sel_hi:[1,0]
	v_cvt_pk_bf16_f32 v52, v90, v91
	v_cvt_pk_bf16_f32 v53, v92, v93
	global_store_dwordx4 v[56:57], v[48:51], off
	global_store_dwordx2 v[58:59], v[52:53], off
	v_lshl_add_u64 v[56:57], v[56:57], 0, s[12:13]
	v_lshl_add_u64 v[58:59], v[58:59], 0, s[14:15]
	s_waitcnt vmcnt(30)
	v_pk_mul_f32 v[60:61], v[94:95], s[90:91] op_sel_hi:[1,0]
	v_pk_mul_f32 v[62:63], v[96:97], s[90:91] op_sel_hi:[1,0]
	v_cvt_pk_bf16_f32 v64, v94, v95
	v_cvt_pk_bf16_f32 v65, v96, v97
	global_store_dwordx4 v[56:57], v[60:63], off
	global_store_dwordx2 v[58:59], v[64:65], off
	v_lshl_add_u64 v[56:57], v[56:57], 0, s[12:13]
	v_lshl_add_u64 v[58:59], v[58:59], 0, s[14:15]
	s_mov_b64 s[12:13], 0x400000
	v_lshl_add_u64 v[6:7], v[4:5], 0, s[12:13]
	s_mov_b64 s[8:9], 0x410000
	v_cmp_gt_u64_e32 vcc, s[8:9], v[6:7]
	s_and_saveexec_b64 s[8:9], vcc
	s_cbranch_execz .LBB0_877
	v_readlane_b32 s2, v254, 56
	s_mov_b64 s[10:11], 0
	v_lshl_add_u32 v9, v0, 2, s2
	s_branch .LBB0_871

; DI const float* INP(const Args& a, int i) { asm volatile("" : "+s"(i)); return a.in[i]; }
; DI void prep_phase(LAS unsigned char* lds, const Args& a) {
;     ...
;     for (size_t i = gt; i < (size_t)DEPTH * 128 * 2 * QKVD; i += gs) { const size_t lb = i / (2 * QKVD), rem = i % (2 * QKVD); a.out[OUT_CS + lb * 3 * QKVD + rem] = INP(a, 3)[lb * 3 * QKVD + QKVD + rem]; }
;     for (size_t i = gt; i < (size_t)DEPTH * 128 * 14 * 512; i += gs) { const size_t lb = i / (14 * 512), rem = i % (14 * 512); a.out[OUT_PS + lb * 15 * 512 + rem] = INP(a, 4)[lb * 15 * 512 + 512 + rem]; }
.LBB0_877:
	s_or_b64 exec, exec, s[8:9]
	s_load_dwordx2 s[8:9], s[0:1], 0x18
	s_load_dwordx2 s[10:11], s[0:1], 0x20
	s_mov_b32 s2, 0xaaaaaaab
	s_mov_b32 s16, 0x24924925
	s_add_u32 s12, s20, 0xca00000
	s_addc_u32 s13, s21, 0
	s_add_u32 s14, s20, 0xd300000
	s_addc_u32 s15, s21, 0
	s_waitcnt lgkmcnt(0)
	s_add_u32 s8, s8, 0x1800
	s_addc_u32 s9, s9, 0
	v_mov_b32_e32 v98, v4
	v_mul_hi_u32 v99, v98, s2
	v_lshrrev_b32_e32 v99, 9, v99
	v_mul_u32_u24_e32 v100, 0x300, v99
	v_sub_u32_e32 v100, v98, v100
	v_lshlrev_b32_e32 v100, 4, v100
	v_mul_u32_u24_e32 v99, 0x4800, v99
	v_add_u32_e32 v100, v99, v100
	v_add_u32_e32 v98, 0x20000, v4
	v_mul_hi_u32 v99, v98, s2
	v_lshrrev_b32_e32 v99, 9, v99
	v_mul_u32_u24_e32 v101, 0x300, v99
	v_sub_u32_e32 v101, v98, v101
	v_lshlrev_b32_e32 v101, 4, v101
	v_mul_u32_u24_e32 v99, 0x4800, v99
	v_add_u32_e32 v101, v99, v101
	v_add_u32_e32 v98, 0x40000, v4
	v_mul_hi_u32 v99, v98, s2
	v_lshrrev_b32_e32 v99, 9, v99
	v_mul_u32_u24_e32 v102, 0x300, v99
	v_sub_u32_e32 v102, v98, v102
	v_lshlrev_b32_e32 v102, 4, v102
	v_mul_u32_u24_e32 v99, 0x4800, v99
	v_add_u32_e32 v102, v99, v102
	v_mov_b32_e32 v128, v100
	v_lshl_add_u64 v[110:111], s[8:9], 0, v[128:129]
	global_load_dwordx4 v[16:19], v[110:111], off
	v_mov_b32_e32 v128, v101
	v_lshl_add_u64 v[110:111], s[8:9], 0, v[128:129]
	global_load_dwordx4 v[20:23], v[110:111], off
	v_mov_b32_e32 v128, v102
	v_lshl_add_u64 v[110:111], s[8:9], 0, v[128:129]
	global_load_dwordx4 v[24:27], v[110:111], off
	v_mov_b32_e32 v98, v4
	v_lshrrev_b32_e32 v99, 8, v98
	v_mul_hi_u32 v99, v99, s16
	v_mul_u32_u24_e32 v103, 0x700, v99
	v_sub_u32_e32 v103, v98, v103
	v_lshlrev_b32_e32 v103, 4, v103
	v_mul_u32_u24_e32 v99, 0x7800, v99
	v_add_u32_e32 v103, v99, v103
	v_add_u32_e32 v98, 0x20000, v4
	v_lshrrev_b32_e32 v99, 8, v98
	v_mul_hi_u32 v99, v99, s16
	v_mul_u32_u24_e32 v104, 0x700, v99
	v_sub_u32_e32 v104, v98, v104
	v_lshlrev_b32_e32 v104, 4, v104
	v_mul_u32_u24_e32 v99, 0x7800, v99
	v_add_u32_e32 v104, v99, v104
	v_add_u32_e32 v98, 0x40000, v4
	v_lshrrev_b32_e32 v99, 8, v98
	v_mul_hi_u32 v99, v99, s16
	v_mul_u32_u24_e32 v105, 0x700, v99
	v_sub_u32_e32 v105, v98, v105
	v_lshlrev_b32_e32 v105, 4, v105
	v_mul_u32_u24_e32 v99, 0x7800, v99
	v_add_u32_e32 v105, v99, v105
	v_add_u32_e32 v98, 0x60000, v4
	v_lshrrev_b32_e32 v99, 8, v98
	v_mul_hi_u32 v99, v99, s16
	v_mul_u32_u24_e32 v106, 0x700, v99
	v_sub_u32_e32 v106, v98, v106
	v_lshlrev_b32_e32 v106, 4, v106
	v_mul_u32_u24_e32 v99, 0x7800, v99
	v_add_u32_e32 v106, v99, v106
	v_add_u32_e32 v98, 0x80000, v4
	v_lshrrev_b32_e32 v99, 8, v98
	v_mul_hi_u32 v99, v99, s16
	v_mul_u32_u24_e32 v107, 0x700, v99
	v_sub_u32_e32 v107, v98, v107
	v_lshlrev_b32_e32 v107, 4, v107
	v_mul_u32_u24_e32 v99, 0x7800, v99
	v_add_u32_e32 v107, v99, v107
	v_add_u32_e32 v98, 0xa0000, v4
	v_lshrrev_b32_e32 v99, 8, v98
	v_mul_hi_u32 v99, v99, s16
	v_mul_u32_u24_e32 v108, 0x700, v99
	v_sub_u32_e32 v108, v98, v108
	v_lshlrev_b32_e32 v108, 4, v108
	v_mul_u32_u24_e32 v99, 0x7800, v99
	v_add_u32_e32 v108, v99, v108
	v_add_u32_e32 v98, 0xc0000, v4
	v_lshrrev_b32_e32 v99, 8, v98
	v_mul_hi_u32 v99, v99, s16
	v_mul_u32_u24_e32 v109, 0x700, v99
	v_sub_u32_e32 v109, v98, v109
	v_lshlrev_b32_e32 v109, 4, v109
	v_mul_u32_u24_e32 v99, 0x7800, v99
	v_add_u32_e32 v109, v99, v109
	v_mov_b32_e32 v128, v103
	v_lshl_add_u64 v[110:111], s[10:11], 0, v[128:129]
	global_load_dwordx4 v[28:31], v[110:111], off offset:2048
	v_mov_b32_e32 v128, v104
	v_lshl_add_u64 v[110:111], s[10:11], 0, v[128:129]
	global_load_dwordx4 v[32:35], v[110:111], off offset:2048
	v_mov_b32_e32 v128, v105
	v_lshl_add_u64 v[110:111], s[10:11], 0, v[128:129]
	global_load_dwordx4 v[36:39], v[110:111], off offset:2048
	v_mov_b32_e32 v128, v106
	v_lshl_add_u64 v[110:111], s[10:11], 0, v[128:129]
	global_load_dwordx4 v[40:43], v[110:111], off offset:2048
	v_mov_b32_e32 v128, v107
	v_lshl_add_u64 v[110:111], s[10:11], 0, v[128:129]
	global_load_dwordx4 v[44:47], v[110:111], off offset:2048
	v_mov_b32_e32 v128, v108
	v_lshl_add_u64 v[110:111], s[10:11], 0, v[128:129]
	global_load_dwordx4 v[48:51], v[110:111], off offset:2048
	v_mov_b32_e32 v128, v109
	v_lshl_add_u64 v[110:111], s[10:11], 0, v[128:129]
	global_load_dwordx4 v[52:55], v[110:111], off offset:2048
	v_mov_b32_e32 v128, v100
	v_lshl_add_u64 v[110:111], s[12:13], 0, v[128:129]
	s_waitcnt vmcnt(9)
	global_store_dwordx4 v[110:111], v[16:19], off
	v_mov_b32_e32 v128, v101
	v_lshl_add_u64 v[110:111], s[12:13], 0, v[128:129]
	s_waitcnt vmcnt(9)
	global_store_dwordx4 v[110:111], v[20:23], off
	v_mov_b32_e32 v128, v102
	v_lshl_add_u64 v[110:111], s[12:13], 0, v[128:129]
	s_waitcnt vmcnt(9)
	global_store_dwordx4 v[110:111], v[24:27], off
	v_mov_b32_e32 v128, v103
	v_lshl_add_u64 v[110:111], s[14:15], 0, v[128:129]
	s_waitcnt vmcnt(9)
	global_store_dwordx4 v[110:111], v[28:31], off
	v_mov_b32_e32 v128, v104
	v_lshl_add_u64 v[110:111], s[14:15], 0, v[128:129]
	s_waitcnt vmcnt(9)
	global_store_dwordx4 v[110:111], v[32:35], off
	v_mov_b32_e32 v128, v105
	v_lshl_add_u64 v[110:111], s[14:15], 0, v[128:129]
	s_waitcnt vmcnt(9)
	global_store_dwordx4 v[110:111], v[36:39], off
	v_mov_b32_e32 v128, v106
	v_lshl_add_u64 v[110:111], s[14:15], 0, v[128:129]
	s_waitcnt vmcnt(9)
	global_store_dwordx4 v[110:111], v[40:43], off
	v_mov_b32_e32 v128, v107
	v_lshl_add_u64 v[110:111], s[14:15], 0, v[128:129]
	s_waitcnt vmcnt(9)
	global_store_dwordx4 v[110:111], v[44:47], off
	v_mov_b32_e32 v128, v108
	v_lshl_add_u64 v[110:111], s[14:15], 0, v[128:129]
	s_waitcnt vmcnt(9)
	global_store_dwordx4 v[110:111], v[48:51], off
	v_mov_b32_e32 v128, v109
	v_lshl_add_u64 v[110:111], s[14:15], 0, v[128:129]
	s_waitcnt vmcnt(9)
	global_store_dwordx4 v[110:111], v[52:55], off
	s_branch .LBB0_8
